# full-line Wout+Down epilogues with the bpermute stage software-pipelined one group ahead
# baseline (speedup 1.0000x reference)
;   DI void operator()(const pg8::f32x4 (&acc)[2][2][4][2], const pg8::Unit& u, int wr, int wc, int fr, int fq) const {
;     const int row0 = u.pm * 256 + wr * 64 + fr, col0 = u.pn * 256 + wc * 32 + 8 * fq;
;     const int b = (u.pm * 256) / TT;
; #pragma unroll
;     for (int ai = 0; ai < 2; ++ai)
; #pragma unroll
;       for (int m = 0; m < 4; ++m) {
;         const int row = row0 + ai * 128 + m * 16;
;         const int t = row - b * TT;
;         const bool isc = t >= TL;
;         float* dst = isc ? xc + ((size_t)b * TC + (t - TL)) * DM : xout + ((size_t)b * TL + t) * DM;
;         const float* src = src_input ? (isc ? cin + ((size_t)b * TC + (t - TL)) * DM : xin + ((size_t)b * TL + t) * DM) : dst;
;         const float* gate = modl + (size_t)(isc ? 16 : b) * 6144 + gi * DM;
; #pragma unroll
;         for (int bj = 0; bj < 2; ++bj) {
;           const int col = col0 + bj * 128;
; #pragma unroll
;           for (int n = 0; n < 2; ++n) {
;             pg8::f32x4 sv = *(const pg8::f32x4*)(src + col + 4 * n);
;             pg8::f32x4 gv = *(const pg8::f32x4*)(gate + col + 4 * n);
;             pg8::f32x4 o = sv + gv * acc[ai][bj][m][n];
;             *(pg8::f32x4*)(dst + col + 4 * n) = o;
;           }
;         }
;       }
;   }
.LBB0_1141:
	v_lshl_or_b32 v142, s30, 8, v150
	v_mov_b32_e32 v141, s34
	v_ashrrev_i32_e32 v143, 31, v142
	v_cndmask_b32_e64 v141, v141, 16, s[8:9]
	v_mov_b64_e32 v[154:155], s[20:21]
	s_movk_i32 s8, 0x6000
	v_lshlrev_b64 v[142:143], 2, v[142:143]
	v_mad_i64_i32 v[154:155], s[8:9], v141, s8, v[154:155]
	v_lshl_add_u64 v[162:163], v[146:147], 0, v[142:143]
	v_lshl_add_u64 v[164:165], v[154:155], 0, v[142:143]
	v_lshl_add_u64 v[166:167], v[144:145], 0, v[142:143]
	s_mov_b32 s10, 0xaaaaaaaa
	s_mov_b32 s11, 0xaaaaaaaa
	s_mov_b64 s[50:51], 0x10000
	s_mov_b64 s[8:9], 0x50000
	v_and_b32_e32 v158, 63, v182
	v_lshrrev_b32_e32 v159, 3, v158
	v_and_b32_e32 v160, 7, v158
	v_lshrrev_b32_e32 v210, 1, v160
	v_lshl_add_u32 v210, v210, 4, v159
	v_lshlrev_b32_e32 v210, 2, v210
	v_add_u32_e32 v211, 32, v210
	v_lshrrev_b32_e32 v161, 4, v158
	v_and_b32_e32 v168, 15, v158
	v_lshlrev_b32_e32 v169, 4, v160
	v_lshlrev_b32_e32 v161, 5, v161
	v_sub_u32_e32 v169, v169, v161
	v_sub_u32_e32 v170, v159, v168
	v_lshl_add_u32 v170, v170, 12, v169
	v_ashrrev_i32_e32 v171, 31, v170
	v_ashrrev_i32_e32 v168, 31, v169
	v_add_co_u32_e32 v212, vcc, v162, v170
	s_nop 1
	v_addc_co_u32_e32 v213, vcc, v163, v171, vcc
	v_add_co_u32_e32 v216, vcc, v166, v170
	s_nop 1
	v_addc_co_u32_e32 v217, vcc, v167, v171, vcc
	v_lshl_add_u64 v[214:215], v[212:213], 0, s[50:51]
	v_add_co_u32_e32 v214, vcc, 0xffff8000, v214
	s_nop 1
	v_addc_co_u32_e32 v215, vcc, -1, v215, vcc
	v_lshl_add_u64 v[218:219], v[216:217], 0, s[50:51]
	v_add_co_u32_e32 v218, vcc, 0xffff8000, v218
	s_nop 1
	v_addc_co_u32_e32 v219, vcc, -1, v219, vcc
	v_add_co_u32_e32 v164, vcc, v164, v169
	s_nop 1
	v_addc_co_u32_e32 v165, vcc, v165, v168, vcc
	global_load_dwordx4 v[202:205], v[164:165], off
	global_load_dwordx4 v[206:209], v[164:165], off offset:512
	global_load_dwordx4 v[220:223], v[212:213], off
	global_load_dwordx4 v[224:227], v[214:215], off
	global_load_dwordx4 v[228:231], v[212:213], off offset:512
	global_load_dwordx4 v[232:235], v[214:215], off offset:512
	v_lshl_add_u64 v[212:213], v[212:213], 0, s[50:51]
	v_lshl_add_u64 v[214:215], v[214:215], 0, s[50:51]
	global_load_dwordx4 v[236:239], v[212:213], off
	global_load_dwordx4 v[240:243], v[214:215], off
	global_load_dwordx4 v[244:247], v[212:213], off offset:512
	global_load_dwordx4 v[248:251], v[214:215], off offset:512
	ds_bpermute_b32 v140, v210, v124
	ds_bpermute_b32 v144, v210, v120
	ds_bpermute_b32 v141, v210, v125
	ds_bpermute_b32 v145, v210, v121
	ds_bpermute_b32 v142, v210, v126
	ds_bpermute_b32 v146, v210, v122
	ds_bpermute_b32 v143, v210, v127
	ds_bpermute_b32 v147, v210, v123
	ds_bpermute_b32 v172, v211, v124
	ds_bpermute_b32 v176, v211, v120
	ds_bpermute_b32 v173, v211, v125
	ds_bpermute_b32 v177, v211, v121
	ds_bpermute_b32 v174, v211, v126
	ds_bpermute_b32 v178, v211, v122
	ds_bpermute_b32 v175, v211, v127
	ds_bpermute_b32 v179, v211, v123
	s_waitcnt lgkmcnt(8)
	s_waitcnt vmcnt(4)
	v_cndmask_b32_e64 v154, v140, v144, s[10:11]
	v_cndmask_b32_e64 v155, v141, v145, s[10:11]
	v_cndmask_b32_e64 v156, v142, v146, s[10:11]
	v_cndmask_b32_e64 v157, v143, v147, s[10:11]
	v_pk_fma_f32 v[222:223], v[156:157], v[204:205], v[222:223]
	v_pk_fma_f32 v[220:221], v[154:155], v[202:203], v[220:221]
	global_store_dwordx4 v[216:217], v[220:223], off
	ds_bpermute_b32 v140, v210, v116
	ds_bpermute_b32 v144, v210, v112
	ds_bpermute_b32 v141, v210, v117
	ds_bpermute_b32 v145, v210, v113
	ds_bpermute_b32 v142, v210, v118
	ds_bpermute_b32 v146, v210, v114
	ds_bpermute_b32 v143, v210, v119
	ds_bpermute_b32 v147, v210, v115
	s_waitcnt lgkmcnt(8)
	v_cndmask_b32_e64 v154, v172, v176, s[10:11]
	v_cndmask_b32_e64 v155, v173, v177, s[10:11]
	v_cndmask_b32_e64 v156, v174, v178, s[10:11]
	v_cndmask_b32_e64 v157, v175, v179, s[10:11]
	v_pk_fma_f32 v[226:227], v[156:157], v[204:205], v[226:227]
	v_pk_fma_f32 v[224:225], v[154:155], v[202:203], v[224:225]
	global_store_dwordx4 v[218:219], v[224:227], off
	ds_bpermute_b32 v172, v211, v116
	ds_bpermute_b32 v176, v211, v112
	ds_bpermute_b32 v173, v211, v117
	ds_bpermute_b32 v177, v211, v113
	ds_bpermute_b32 v174, v211, v118
	ds_bpermute_b32 v178, v211, v114
	ds_bpermute_b32 v175, v211, v119
	ds_bpermute_b32 v179, v211, v115
	s_waitcnt lgkmcnt(8)
	v_cndmask_b32_e64 v154, v140, v144, s[10:11]
	v_cndmask_b32_e64 v155, v141, v145, s[10:11]
	v_cndmask_b32_e64 v156, v142, v146, s[10:11]
	v_cndmask_b32_e64 v157, v143, v147, s[10:11]
	v_pk_fma_f32 v[230:231], v[156:157], v[208:209], v[230:231]
	v_pk_fma_f32 v[228:229], v[154:155], v[206:207], v[228:229]
	global_store_dwordx4 v[216:217], v[228:231], off offset:512
	ds_bpermute_b32 v140, v210, v108
	ds_bpermute_b32 v144, v210, v104
	ds_bpermute_b32 v141, v210, v109
	ds_bpermute_b32 v145, v210, v105
	ds_bpermute_b32 v142, v210, v110
	ds_bpermute_b32 v146, v210, v106
	ds_bpermute_b32 v143, v210, v111
	ds_bpermute_b32 v147, v210, v107
	s_waitcnt lgkmcnt(8)
	v_cndmask_b32_e64 v154, v172, v176, s[10:11]
	v_cndmask_b32_e64 v155, v173, v177, s[10:11]
	v_cndmask_b32_e64 v156, v174, v178, s[10:11]
	v_cndmask_b32_e64 v157, v175, v179, s[10:11]
	v_pk_fma_f32 v[234:235], v[156:157], v[208:209], v[234:235]
	v_pk_fma_f32 v[232:233], v[154:155], v[206:207], v[232:233]
	global_store_dwordx4 v[218:219], v[232:235], off offset:512
	v_lshl_add_u64 v[212:213], v[212:213], 0, s[50:51]
	v_lshl_add_u64 v[214:215], v[214:215], 0, s[50:51]
	global_load_dwordx4 v[220:223], v[212:213], off
	global_load_dwordx4 v[224:227], v[214:215], off
	global_load_dwordx4 v[228:231], v[212:213], off offset:512
	global_load_dwordx4 v[232:235], v[214:215], off offset:512
	ds_bpermute_b32 v172, v211, v108
	ds_bpermute_b32 v176, v211, v104
	ds_bpermute_b32 v173, v211, v109
	ds_bpermute_b32 v177, v211, v105
	ds_bpermute_b32 v174, v211, v110
	ds_bpermute_b32 v178, v211, v106
	ds_bpermute_b32 v175, v211, v111
	ds_bpermute_b32 v179, v211, v107
	s_waitcnt lgkmcnt(8)
;   DI void operator()(const pg8::f32x4 (&acc)[2][2][4][2], const pg8::Unit& u, int wr, int wc, int fr, int fq) const {
;     const int row0 = u.pm * 256 + wr * 64 + fr, col0 = u.pn * 256 + wc * 32 + 8 * fq;
;     const int b = (u.pm * 256) / TT;
; #pragma unroll
;     for (int ai = 0; ai < 2; ++ai)
; #pragma unroll
;       for (int m = 0; m < 4; ++m) {
;         const int row = row0 + ai * 128 + m * 16;
;         const int t = row - b * TT;
;         const bool isc = t >= TL;
;         float* dst = isc ? xc + ((size_t)b * TC + (t - TL)) * DM : xout + ((size_t)b * TL + t) * DM;
;         const float* src = src_input ? (isc ? cin + ((size_t)b * TC + (t - TL)) * DM : xin + ((size_t)b * TL + t) * DM) : dst;
;         const float* gate = modl + (size_t)(isc ? 16 : b) * 6144 + gi * DM;
; #pragma unroll
;         for (int bj = 0; bj < 2; ++bj) {
;           const int col = col0 + bj * 128;
; #pragma unroll
;           for (int n = 0; n < 2; ++n) {
;             pg8::f32x4 sv = *(const pg8::f32x4*)(src + col + 4 * n);
;             pg8::f32x4 gv = *(const pg8::f32x4*)(gate + col + 4 * n);
;             pg8::f32x4 o = sv + gv * acc[ai][bj][m][n];
;             *(pg8::f32x4*)(dst + col + 4 * n) = o;
;           }
;         }
;       }
;   }
	s_waitcnt vmcnt(8)
	v_lshl_add_u64 v[216:217], v[216:217], 0, s[50:51]
	v_lshl_add_u64 v[218:219], v[218:219], 0, s[50:51]
	v_cndmask_b32_e64 v154, v140, v144, s[10:11]
	v_cndmask_b32_e64 v155, v141, v145, s[10:11]
	v_cndmask_b32_e64 v156, v142, v146, s[10:11]
	v_cndmask_b32_e64 v157, v143, v147, s[10:11]
	v_pk_fma_f32 v[238:239], v[156:157], v[204:205], v[238:239]
	v_pk_fma_f32 v[236:237], v[154:155], v[202:203], v[236:237]
	global_store_dwordx4 v[216:217], v[236:239], off
	ds_bpermute_b32 v140, v210, v100
	ds_bpermute_b32 v144, v210, v96
	ds_bpermute_b32 v141, v210, v101
	ds_bpermute_b32 v145, v210, v97
	ds_bpermute_b32 v142, v210, v102
	ds_bpermute_b32 v146, v210, v98
	ds_bpermute_b32 v143, v210, v103
	ds_bpermute_b32 v147, v210, v99
	s_waitcnt lgkmcnt(8)
	v_cndmask_b32_e64 v154, v172, v176, s[10:11]
	v_cndmask_b32_e64 v155, v173, v177, s[10:11]
	v_cndmask_b32_e64 v156, v174, v178, s[10:11]
	v_cndmask_b32_e64 v157, v175, v179, s[10:11]
	v_pk_fma_f32 v[242:243], v[156:157], v[204:205], v[242:243]
	v_pk_fma_f32 v[240:241], v[154:155], v[202:203], v[240:241]
	global_store_dwordx4 v[218:219], v[240:243], off
	ds_bpermute_b32 v172, v211, v100
	ds_bpermute_b32 v176, v211, v96
	ds_bpermute_b32 v173, v211, v101
	ds_bpermute_b32 v177, v211, v97
	ds_bpermute_b32 v174, v211, v102
	ds_bpermute_b32 v178, v211, v98
	ds_bpermute_b32 v175, v211, v103
	ds_bpermute_b32 v179, v211, v99
	s_waitcnt lgkmcnt(8)
	v_cndmask_b32_e64 v154, v140, v144, s[10:11]
	v_cndmask_b32_e64 v155, v141, v145, s[10:11]
	v_cndmask_b32_e64 v156, v142, v146, s[10:11]
	v_cndmask_b32_e64 v157, v143, v147, s[10:11]
	v_pk_fma_f32 v[246:247], v[156:157], v[208:209], v[246:247]
	v_pk_fma_f32 v[244:245], v[154:155], v[206:207], v[244:245]
	global_store_dwordx4 v[216:217], v[244:247], off offset:512
	ds_bpermute_b32 v140, v210, v92
	ds_bpermute_b32 v144, v210, v88
	ds_bpermute_b32 v141, v210, v93
	ds_bpermute_b32 v145, v210, v89
	ds_bpermute_b32 v142, v210, v94
	ds_bpermute_b32 v146, v210, v90
	ds_bpermute_b32 v143, v210, v95
	ds_bpermute_b32 v147, v210, v91
	s_waitcnt lgkmcnt(8)
	v_cndmask_b32_e64 v154, v172, v176, s[10:11]
	v_cndmask_b32_e64 v155, v173, v177, s[10:11]
	v_cndmask_b32_e64 v156, v174, v178, s[10:11]
	v_cndmask_b32_e64 v157, v175, v179, s[10:11]
	v_pk_fma_f32 v[250:251], v[156:157], v[208:209], v[250:251]
	v_pk_fma_f32 v[248:249], v[154:155], v[206:207], v[248:249]
	global_store_dwordx4 v[218:219], v[248:251], off offset:512
	v_lshl_add_u64 v[212:213], v[212:213], 0, s[50:51]
	v_lshl_add_u64 v[214:215], v[214:215], 0, s[50:51]
	global_load_dwordx4 v[236:239], v[212:213], off
	global_load_dwordx4 v[240:243], v[214:215], off
	global_load_dwordx4 v[244:247], v[212:213], off offset:512
	global_load_dwordx4 v[248:251], v[214:215], off offset:512
	ds_bpermute_b32 v172, v211, v92
	ds_bpermute_b32 v176, v211, v88
	ds_bpermute_b32 v173, v211, v93
	ds_bpermute_b32 v177, v211, v89
	ds_bpermute_b32 v174, v211, v94
	ds_bpermute_b32 v178, v211, v90
	ds_bpermute_b32 v175, v211, v95
	ds_bpermute_b32 v179, v211, v91
	s_waitcnt lgkmcnt(8)
	s_waitcnt vmcnt(8)
	v_lshl_add_u64 v[216:217], v[216:217], 0, s[50:51]
	v_lshl_add_u64 v[218:219], v[218:219], 0, s[50:51]
	v_cndmask_b32_e64 v154, v140, v144, s[10:11]
	v_cndmask_b32_e64 v155, v141, v145, s[10:11]
	v_cndmask_b32_e64 v156, v142, v146, s[10:11]
	v_cndmask_b32_e64 v157, v143, v147, s[10:11]
	v_pk_fma_f32 v[222:223], v[156:157], v[204:205], v[222:223]
	v_pk_fma_f32 v[220:221], v[154:155], v[202:203], v[220:221]
	global_store_dwordx4 v[216:217], v[220:223], off
	ds_bpermute_b32 v140, v210, v84
	ds_bpermute_b32 v144, v210, v80
	ds_bpermute_b32 v141, v210, v85
	ds_bpermute_b32 v145, v210, v81
	ds_bpermute_b32 v142, v210, v86
	ds_bpermute_b32 v146, v210, v82
	ds_bpermute_b32 v143, v210, v87
	ds_bpermute_b32 v147, v210, v83
	s_waitcnt lgkmcnt(8)
	v_cndmask_b32_e64 v154, v172, v176, s[10:11]
	v_cndmask_b32_e64 v155, v173, v177, s[10:11]
	v_cndmask_b32_e64 v156, v174, v178, s[10:11]
	v_cndmask_b32_e64 v157, v175, v179, s[10:11]
	v_pk_fma_f32 v[226:227], v[156:157], v[204:205], v[226:227]
	v_pk_fma_f32 v[224:225], v[154:155], v[202:203], v[224:225]
	global_store_dwordx4 v[218:219], v[224:227], off
	ds_bpermute_b32 v172, v211, v84
	ds_bpermute_b32 v176, v211, v80
	ds_bpermute_b32 v173, v211, v85
	ds_bpermute_b32 v177, v211, v81
	ds_bpermute_b32 v174, v211, v86
	ds_bpermute_b32 v178, v211, v82
	ds_bpermute_b32 v175, v211, v87
	ds_bpermute_b32 v179, v211, v83
	s_waitcnt lgkmcnt(8)
	v_cndmask_b32_e64 v154, v140, v144, s[10:11]
	v_cndmask_b32_e64 v155, v141, v145, s[10:11]
	v_cndmask_b32_e64 v156, v142, v146, s[10:11]
	v_cndmask_b32_e64 v157, v143, v147, s[10:11]
	v_pk_fma_f32 v[230:231], v[156:157], v[208:209], v[230:231]
	v_pk_fma_f32 v[228:229], v[154:155], v[206:207], v[228:229]
	global_store_dwordx4 v[216:217], v[228:231], off offset:512
	ds_bpermute_b32 v140, v210, v76
	ds_bpermute_b32 v144, v210, v72
	ds_bpermute_b32 v141, v210, v77
	ds_bpermute_b32 v145, v210, v73
	ds_bpermute_b32 v142, v210, v78
	ds_bpermute_b32 v146, v210, v74
	ds_bpermute_b32 v143, v210, v79
	ds_bpermute_b32 v147, v210, v75
	s_waitcnt lgkmcnt(8)
	v_cndmask_b32_e64 v154, v172, v176, s[10:11]
	v_cndmask_b32_e64 v155, v173, v177, s[10:11]
	v_cndmask_b32_e64 v156, v174, v178, s[10:11]
	v_cndmask_b32_e64 v157, v175, v179, s[10:11]
	v_pk_fma_f32 v[234:235], v[156:157], v[208:209], v[234:235]
	v_pk_fma_f32 v[232:233], v[154:155], v[206:207], v[232:233]
	global_store_dwordx4 v[218:219], v[232:235], off offset:512
	v_lshl_add_u64 v[212:213], v[212:213], 0, s[8:9]
	v_lshl_add_u64 v[214:215], v[214:215], 0, s[8:9]
	global_load_dwordx4 v[220:223], v[212:213], off
	global_load_dwordx4 v[224:227], v[214:215], off
	global_load_dwordx4 v[228:231], v[212:213], off offset:512
	global_load_dwordx4 v[232:235], v[214:215], off offset:512
	ds_bpermute_b32 v172, v211, v76
	ds_bpermute_b32 v176, v211, v72
	ds_bpermute_b32 v173, v211, v77
	ds_bpermute_b32 v177, v211, v73
	ds_bpermute_b32 v174, v211, v78
	ds_bpermute_b32 v178, v211, v74
	ds_bpermute_b32 v175, v211, v79
	ds_bpermute_b32 v179, v211, v75
	s_waitcnt lgkmcnt(8)
;   DI void operator()(const pg8::f32x4 (&acc)[2][2][4][2], const pg8::Unit& u, int wr, int wc, int fr, int fq) const {
;     const int row0 = u.pm * 256 + wr * 64 + fr, col0 = u.pn * 256 + wc * 32 + 8 * fq;
;     const int b = (u.pm * 256) / TT;
; #pragma unroll
;     for (int ai = 0; ai < 2; ++ai)
; #pragma unroll
;       for (int m = 0; m < 4; ++m) {
;         const int row = row0 + ai * 128 + m * 16;
;         const int t = row - b * TT;
;         const bool isc = t >= TL;
;         float* dst = isc ? xc + ((size_t)b * TC + (t - TL)) * DM : xout + ((size_t)b * TL + t) * DM;
;         const float* src = src_input ? (isc ? cin + ((size_t)b * TC + (t - TL)) * DM : xin + ((size_t)b * TL + t) * DM) : dst;
;         const float* gate = modl + (size_t)(isc ? 16 : b) * 6144 + gi * DM;
; #pragma unroll
;         for (int bj = 0; bj < 2; ++bj) {
;           const int col = col0 + bj * 128;
; #pragma unroll
;           for (int n = 0; n < 2; ++n) {
;             pg8::f32x4 sv = *(const pg8::f32x4*)(src + col + 4 * n);
;             pg8::f32x4 gv = *(const pg8::f32x4*)(gate + col + 4 * n);
;             pg8::f32x4 o = sv + gv * acc[ai][bj][m][n];
;             *(pg8::f32x4*)(dst + col + 4 * n) = o;
;           }
;         }
;       }
;   }
	s_waitcnt vmcnt(8)
	v_lshl_add_u64 v[216:217], v[216:217], 0, s[50:51]
	v_lshl_add_u64 v[218:219], v[218:219], 0, s[50:51]
	v_cndmask_b32_e64 v154, v140, v144, s[10:11]
	v_cndmask_b32_e64 v155, v141, v145, s[10:11]
	v_cndmask_b32_e64 v156, v142, v146, s[10:11]
	v_cndmask_b32_e64 v157, v143, v147, s[10:11]
	v_pk_fma_f32 v[238:239], v[156:157], v[204:205], v[238:239]
	v_pk_fma_f32 v[236:237], v[154:155], v[202:203], v[236:237]
	global_store_dwordx4 v[216:217], v[236:239], off
	ds_bpermute_b32 v140, v210, v68
	ds_bpermute_b32 v144, v210, v64
	ds_bpermute_b32 v141, v210, v69
	ds_bpermute_b32 v145, v210, v65
	ds_bpermute_b32 v142, v210, v70
	ds_bpermute_b32 v146, v210, v66
	ds_bpermute_b32 v143, v210, v71
	ds_bpermute_b32 v147, v210, v67
	s_waitcnt lgkmcnt(8)
	v_cndmask_b32_e64 v154, v172, v176, s[10:11]
	v_cndmask_b32_e64 v155, v173, v177, s[10:11]
	v_cndmask_b32_e64 v156, v174, v178, s[10:11]
	v_cndmask_b32_e64 v157, v175, v179, s[10:11]
	v_pk_fma_f32 v[242:243], v[156:157], v[204:205], v[242:243]
	v_pk_fma_f32 v[240:241], v[154:155], v[202:203], v[240:241]
	global_store_dwordx4 v[218:219], v[240:243], off
	ds_bpermute_b32 v172, v211, v68
	ds_bpermute_b32 v176, v211, v64
	ds_bpermute_b32 v173, v211, v69
	ds_bpermute_b32 v177, v211, v65
	ds_bpermute_b32 v174, v211, v70
	ds_bpermute_b32 v178, v211, v66
	ds_bpermute_b32 v175, v211, v71
	ds_bpermute_b32 v179, v211, v67
	s_waitcnt lgkmcnt(8)
	v_cndmask_b32_e64 v154, v140, v144, s[10:11]
	v_cndmask_b32_e64 v155, v141, v145, s[10:11]
	v_cndmask_b32_e64 v156, v142, v146, s[10:11]
	v_cndmask_b32_e64 v157, v143, v147, s[10:11]
	v_pk_fma_f32 v[246:247], v[156:157], v[208:209], v[246:247]
	v_pk_fma_f32 v[244:245], v[154:155], v[206:207], v[244:245]
	global_store_dwordx4 v[216:217], v[244:247], off offset:512
	ds_bpermute_b32 v140, v210, v60
	ds_bpermute_b32 v144, v210, v56
	ds_bpermute_b32 v141, v210, v61
	ds_bpermute_b32 v145, v210, v57
	ds_bpermute_b32 v142, v210, v62
	ds_bpermute_b32 v146, v210, v58
	ds_bpermute_b32 v143, v210, v63
	ds_bpermute_b32 v147, v210, v59
	s_waitcnt lgkmcnt(8)
	v_cndmask_b32_e64 v154, v172, v176, s[10:11]
	v_cndmask_b32_e64 v155, v173, v177, s[10:11]
	v_cndmask_b32_e64 v156, v174, v178, s[10:11]
	v_cndmask_b32_e64 v157, v175, v179, s[10:11]
	v_pk_fma_f32 v[250:251], v[156:157], v[208:209], v[250:251]
	v_pk_fma_f32 v[248:249], v[154:155], v[206:207], v[248:249]
	global_store_dwordx4 v[218:219], v[248:251], off offset:512
	v_lshl_add_u64 v[212:213], v[212:213], 0, s[50:51]
	v_lshl_add_u64 v[214:215], v[214:215], 0, s[50:51]
	global_load_dwordx4 v[236:239], v[212:213], off
	global_load_dwordx4 v[240:243], v[214:215], off
	global_load_dwordx4 v[244:247], v[212:213], off offset:512
	global_load_dwordx4 v[248:251], v[214:215], off offset:512
	ds_bpermute_b32 v172, v211, v60
	ds_bpermute_b32 v176, v211, v56
	ds_bpermute_b32 v173, v211, v61
	ds_bpermute_b32 v177, v211, v57
	ds_bpermute_b32 v174, v211, v62
	ds_bpermute_b32 v178, v211, v58
	ds_bpermute_b32 v175, v211, v63
	ds_bpermute_b32 v179, v211, v59
	s_waitcnt lgkmcnt(8)
	s_waitcnt vmcnt(8)
	v_lshl_add_u64 v[216:217], v[216:217], 0, s[8:9]
	v_lshl_add_u64 v[218:219], v[218:219], 0, s[8:9]
	v_cndmask_b32_e64 v154, v140, v144, s[10:11]
	v_cndmask_b32_e64 v155, v141, v145, s[10:11]
	v_cndmask_b32_e64 v156, v142, v146, s[10:11]
	v_cndmask_b32_e64 v157, v143, v147, s[10:11]
	v_pk_fma_f32 v[222:223], v[156:157], v[204:205], v[222:223]
	v_pk_fma_f32 v[220:221], v[154:155], v[202:203], v[220:221]
	global_store_dwordx4 v[216:217], v[220:223], off
	ds_bpermute_b32 v140, v210, v52
	ds_bpermute_b32 v144, v210, v48
	ds_bpermute_b32 v141, v210, v53
	ds_bpermute_b32 v145, v210, v49
	ds_bpermute_b32 v142, v210, v54
	ds_bpermute_b32 v146, v210, v50
	ds_bpermute_b32 v143, v210, v55
	ds_bpermute_b32 v147, v210, v51
	s_waitcnt lgkmcnt(8)
	v_cndmask_b32_e64 v154, v172, v176, s[10:11]
	v_cndmask_b32_e64 v155, v173, v177, s[10:11]
	v_cndmask_b32_e64 v156, v174, v178, s[10:11]
	v_cndmask_b32_e64 v157, v175, v179, s[10:11]
	v_pk_fma_f32 v[226:227], v[156:157], v[204:205], v[226:227]
	v_pk_fma_f32 v[224:225], v[154:155], v[202:203], v[224:225]
	global_store_dwordx4 v[218:219], v[224:227], off
	ds_bpermute_b32 v172, v211, v52
	ds_bpermute_b32 v176, v211, v48
	ds_bpermute_b32 v173, v211, v53
	ds_bpermute_b32 v177, v211, v49
	ds_bpermute_b32 v174, v211, v54
	ds_bpermute_b32 v178, v211, v50
	ds_bpermute_b32 v175, v211, v55
	ds_bpermute_b32 v179, v211, v51
	s_waitcnt lgkmcnt(8)
	v_cndmask_b32_e64 v154, v140, v144, s[10:11]
	v_cndmask_b32_e64 v155, v141, v145, s[10:11]
	v_cndmask_b32_e64 v156, v142, v146, s[10:11]
	v_cndmask_b32_e64 v157, v143, v147, s[10:11]
	v_pk_fma_f32 v[230:231], v[156:157], v[208:209], v[230:231]
	v_pk_fma_f32 v[228:229], v[154:155], v[206:207], v[228:229]
	global_store_dwordx4 v[216:217], v[228:231], off offset:512
	ds_bpermute_b32 v140, v210, v44
	ds_bpermute_b32 v144, v210, v40
	ds_bpermute_b32 v141, v210, v45
	ds_bpermute_b32 v145, v210, v41
	ds_bpermute_b32 v142, v210, v46
	ds_bpermute_b32 v146, v210, v42
	ds_bpermute_b32 v143, v210, v47
	ds_bpermute_b32 v147, v210, v43
	s_waitcnt lgkmcnt(8)
	v_cndmask_b32_e64 v154, v172, v176, s[10:11]
	v_cndmask_b32_e64 v155, v173, v177, s[10:11]
	v_cndmask_b32_e64 v156, v174, v178, s[10:11]
	v_cndmask_b32_e64 v157, v175, v179, s[10:11]
	v_pk_fma_f32 v[234:235], v[156:157], v[208:209], v[234:235]
	v_pk_fma_f32 v[232:233], v[154:155], v[206:207], v[232:233]
	global_store_dwordx4 v[218:219], v[232:235], off offset:512
	v_lshl_add_u64 v[212:213], v[212:213], 0, s[50:51]
	v_lshl_add_u64 v[214:215], v[214:215], 0, s[50:51]
	global_load_dwordx4 v[220:223], v[212:213], off
	global_load_dwordx4 v[224:227], v[214:215], off
	global_load_dwordx4 v[228:231], v[212:213], off offset:512
	global_load_dwordx4 v[232:235], v[214:215], off offset:512
	ds_bpermute_b32 v172, v211, v44
	ds_bpermute_b32 v176, v211, v40
	ds_bpermute_b32 v173, v211, v45
	ds_bpermute_b32 v177, v211, v41
	ds_bpermute_b32 v174, v211, v46
	ds_bpermute_b32 v178, v211, v42
	ds_bpermute_b32 v175, v211, v47
	ds_bpermute_b32 v179, v211, v43
	s_waitcnt lgkmcnt(8)
;   DI void operator()(const pg8::f32x4 (&acc)[2][2][4][2], const pg8::Unit& u, int wr, int wc, int fr, int fq) const {
;     const int row0 = u.pm * 256 + wr * 64 + fr, col0 = u.pn * 256 + wc * 32 + 8 * fq;
;     const int b = (u.pm * 256) / TT;
; #pragma unroll
;     for (int ai = 0; ai < 2; ++ai)
; #pragma unroll
;       for (int m = 0; m < 4; ++m) {
;         const int row = row0 + ai * 128 + m * 16;
;         const int t = row - b * TT;
;         const bool isc = t >= TL;
;         float* dst = isc ? xc + ((size_t)b * TC + (t - TL)) * DM : xout + ((size_t)b * TL + t) * DM;
;         const float* src = src_input ? (isc ? cin + ((size_t)b * TC + (t - TL)) * DM : xin + ((size_t)b * TL + t) * DM) : dst;
;         const float* gate = modl + (size_t)(isc ? 16 : b) * 6144 + gi * DM;
; #pragma unroll
;         for (int bj = 0; bj < 2; ++bj) {
;           const int col = col0 + bj * 128;
; #pragma unroll
;           for (int n = 0; n < 2; ++n) {
;             pg8::f32x4 sv = *(const pg8::f32x4*)(src + col + 4 * n);
;             pg8::f32x4 gv = *(const pg8::f32x4*)(gate + col + 4 * n);
;             pg8::f32x4 o = sv + gv * acc[ai][bj][m][n];
;             *(pg8::f32x4*)(dst + col + 4 * n) = o;
;           }
;         }
;       }
;   }
	s_waitcnt vmcnt(8)
	v_lshl_add_u64 v[216:217], v[216:217], 0, s[50:51]
	v_lshl_add_u64 v[218:219], v[218:219], 0, s[50:51]
	v_cndmask_b32_e64 v154, v140, v144, s[10:11]
	v_cndmask_b32_e64 v155, v141, v145, s[10:11]
	v_cndmask_b32_e64 v156, v142, v146, s[10:11]
	v_cndmask_b32_e64 v157, v143, v147, s[10:11]
	v_pk_fma_f32 v[238:239], v[156:157], v[204:205], v[238:239]
	v_pk_fma_f32 v[236:237], v[154:155], v[202:203], v[236:237]
	global_store_dwordx4 v[216:217], v[236:239], off
	ds_bpermute_b32 v140, v210, v36
	ds_bpermute_b32 v144, v210, v32
	ds_bpermute_b32 v141, v210, v37
	ds_bpermute_b32 v145, v210, v33
	ds_bpermute_b32 v142, v210, v38
	ds_bpermute_b32 v146, v210, v34
	ds_bpermute_b32 v143, v210, v39
	ds_bpermute_b32 v147, v210, v35
	s_waitcnt lgkmcnt(8)
	v_cndmask_b32_e64 v154, v172, v176, s[10:11]
	v_cndmask_b32_e64 v155, v173, v177, s[10:11]
	v_cndmask_b32_e64 v156, v174, v178, s[10:11]
	v_cndmask_b32_e64 v157, v175, v179, s[10:11]
	v_pk_fma_f32 v[242:243], v[156:157], v[204:205], v[242:243]
	v_pk_fma_f32 v[240:241], v[154:155], v[202:203], v[240:241]
	global_store_dwordx4 v[218:219], v[240:243], off
	ds_bpermute_b32 v172, v211, v36
	ds_bpermute_b32 v176, v211, v32
	ds_bpermute_b32 v173, v211, v37
	ds_bpermute_b32 v177, v211, v33
	ds_bpermute_b32 v174, v211, v38
	ds_bpermute_b32 v178, v211, v34
	ds_bpermute_b32 v175, v211, v39
	ds_bpermute_b32 v179, v211, v35
	s_waitcnt lgkmcnt(8)
	v_cndmask_b32_e64 v154, v140, v144, s[10:11]
	v_cndmask_b32_e64 v155, v141, v145, s[10:11]
	v_cndmask_b32_e64 v156, v142, v146, s[10:11]
	v_cndmask_b32_e64 v157, v143, v147, s[10:11]
	v_pk_fma_f32 v[246:247], v[156:157], v[208:209], v[246:247]
	v_pk_fma_f32 v[244:245], v[154:155], v[206:207], v[244:245]
	global_store_dwordx4 v[216:217], v[244:247], off offset:512
	ds_bpermute_b32 v140, v210, v28
	ds_bpermute_b32 v144, v210, v24
	ds_bpermute_b32 v141, v210, v29
	ds_bpermute_b32 v145, v210, v25
	ds_bpermute_b32 v142, v210, v30
	ds_bpermute_b32 v146, v210, v26
	ds_bpermute_b32 v143, v210, v31
	ds_bpermute_b32 v147, v210, v27
	s_waitcnt lgkmcnt(8)
	v_cndmask_b32_e64 v154, v172, v176, s[10:11]
	v_cndmask_b32_e64 v155, v173, v177, s[10:11]
	v_cndmask_b32_e64 v156, v174, v178, s[10:11]
	v_cndmask_b32_e64 v157, v175, v179, s[10:11]
	v_pk_fma_f32 v[250:251], v[156:157], v[208:209], v[250:251]
	v_pk_fma_f32 v[248:249], v[154:155], v[206:207], v[248:249]
	global_store_dwordx4 v[218:219], v[248:251], off offset:512
	v_lshl_add_u64 v[212:213], v[212:213], 0, s[50:51]
	v_lshl_add_u64 v[214:215], v[214:215], 0, s[50:51]
	global_load_dwordx4 v[236:239], v[212:213], off
	global_load_dwordx4 v[240:243], v[214:215], off
	global_load_dwordx4 v[244:247], v[212:213], off offset:512
	global_load_dwordx4 v[248:251], v[214:215], off offset:512
	ds_bpermute_b32 v172, v211, v28
	ds_bpermute_b32 v176, v211, v24
	ds_bpermute_b32 v173, v211, v29
	ds_bpermute_b32 v177, v211, v25
	ds_bpermute_b32 v174, v211, v30
	ds_bpermute_b32 v178, v211, v26
	ds_bpermute_b32 v175, v211, v31
	ds_bpermute_b32 v179, v211, v27
	s_waitcnt lgkmcnt(8)
	s_waitcnt vmcnt(8)
	v_lshl_add_u64 v[216:217], v[216:217], 0, s[50:51]
	v_lshl_add_u64 v[218:219], v[218:219], 0, s[50:51]
	v_cndmask_b32_e64 v154, v140, v144, s[10:11]
	v_cndmask_b32_e64 v155, v141, v145, s[10:11]
	v_cndmask_b32_e64 v156, v142, v146, s[10:11]
	v_cndmask_b32_e64 v157, v143, v147, s[10:11]
	v_pk_fma_f32 v[222:223], v[156:157], v[204:205], v[222:223]
	v_pk_fma_f32 v[220:221], v[154:155], v[202:203], v[220:221]
	global_store_dwordx4 v[216:217], v[220:223], off
	ds_bpermute_b32 v140, v210, v20
	ds_bpermute_b32 v144, v210, v16
	ds_bpermute_b32 v141, v210, v21
	ds_bpermute_b32 v145, v210, v17
	ds_bpermute_b32 v142, v210, v22
	ds_bpermute_b32 v146, v210, v18
	ds_bpermute_b32 v143, v210, v23
	ds_bpermute_b32 v147, v210, v19
	s_waitcnt lgkmcnt(8)
; #define PG8_BAR __builtin_amdgcn_s_barrier()
; template <class Epi, class Sched, bool ALIGN_EPI = false, bool SP2 = false>
; __device__ __forceinline__ void gemm_phase(PG8_LAS unsigned char* lds, const Gemm g, const Sched& S, const Epi& E) {
;     ...
;         if constexpr (!Epi::AFTER_DRAIN) { E(acc, cur, wr, wc, fr, fq); S.done(cur); }
;         if (!has_next) break;
; #pragma unroll
;         for (int a = 0; a < 2; ++a)
; #pragma unroll
;             for (int b = 0; b < 2; ++b)
; #pragma unroll
;                 for (int m = 0; m < 4; ++m)
; #pragma unroll
;                     for (int n = 0; n < 2; ++n) acc[a][b][m][n] = (f32x4){0.f, 0.f, 0.f, 0.f};
;         cur = nxt; cA = nA; cB = nB; ++ui;
;         if constexpr (ALIGN_EPI) { if (wr == 1) PG8_BAR; }
;     }
;   DI void operator()(const pg8::f32x4 (&acc)[2][2][4][2], const pg8::Unit& u, int wr, int wc, int fr, int fq) const {
;     const int row0 = u.pm * 256 + wr * 64 + fr, col0 = u.pn * 256 + wc * 32 + 8 * fq;
;     const int b = (u.pm * 256) / TT;
; #pragma unroll
;     for (int ai = 0; ai < 2; ++ai)
; #pragma unroll
;       for (int m = 0; m < 4; ++m) {
;         const int row = row0 + ai * 128 + m * 16;
;         const int t = row - b * TT;
;         const bool isc = t >= TL;
;         float* dst = isc ? xc + ((size_t)b * TC + (t - TL)) * DM : xout + ((size_t)b * TL + t) * DM;
;         const float* src = src_input ? (isc ? cin + ((size_t)b * TC + (t - TL)) * DM : xin + ((size_t)b * TL + t) * DM) : dst;
;         const float* gate = modl + (size_t)(isc ? 16 : b) * 6144 + gi * DM;
; #pragma unroll
;         for (int bj = 0; bj < 2; ++bj) {
;           const int col = col0 + bj * 128;
; #pragma unroll
;           for (int n = 0; n < 2; ++n) {
;             pg8::f32x4 sv = *(const pg8::f32x4*)(src + col + 4 * n);
;             pg8::f32x4 gv = *(const pg8::f32x4*)(gate + col + 4 * n);
;             pg8::f32x4 o = sv + gv * acc[ai][bj][m][n];
;             *(pg8::f32x4*)(dst + col + 4 * n) = o;
;           }
;         }
;       }
;   }
	v_cndmask_b32_e64 v154, v172, v176, s[10:11]
	v_cndmask_b32_e64 v155, v173, v177, s[10:11]
	v_cndmask_b32_e64 v156, v174, v178, s[10:11]
	v_cndmask_b32_e64 v157, v175, v179, s[10:11]
	v_pk_fma_f32 v[226:227], v[156:157], v[204:205], v[226:227]
	v_pk_fma_f32 v[224:225], v[154:155], v[202:203], v[224:225]
	global_store_dwordx4 v[218:219], v[224:227], off
	ds_bpermute_b32 v172, v211, v20
	ds_bpermute_b32 v176, v211, v16
	ds_bpermute_b32 v173, v211, v21
	ds_bpermute_b32 v177, v211, v17
	ds_bpermute_b32 v174, v211, v22
	ds_bpermute_b32 v178, v211, v18
	ds_bpermute_b32 v175, v211, v23
	ds_bpermute_b32 v179, v211, v19
	s_waitcnt lgkmcnt(8)
	v_cndmask_b32_e64 v154, v140, v144, s[10:11]
	v_cndmask_b32_e64 v155, v141, v145, s[10:11]
	v_cndmask_b32_e64 v156, v142, v146, s[10:11]
	v_cndmask_b32_e64 v157, v143, v147, s[10:11]
	v_pk_fma_f32 v[230:231], v[156:157], v[208:209], v[230:231]
	v_pk_fma_f32 v[228:229], v[154:155], v[206:207], v[228:229]
	global_store_dwordx4 v[216:217], v[228:231], off offset:512
	ds_bpermute_b32 v140, v210, v12
	ds_bpermute_b32 v144, v210, v8
	ds_bpermute_b32 v141, v210, v13
	ds_bpermute_b32 v145, v210, v9
	ds_bpermute_b32 v142, v210, v14
	ds_bpermute_b32 v146, v210, v10
	ds_bpermute_b32 v143, v210, v15
	ds_bpermute_b32 v147, v210, v11
	s_waitcnt lgkmcnt(8)
	v_cndmask_b32_e64 v154, v172, v176, s[10:11]
	v_cndmask_b32_e64 v155, v173, v177, s[10:11]
	v_cndmask_b32_e64 v156, v174, v178, s[10:11]
	v_cndmask_b32_e64 v157, v175, v179, s[10:11]
	v_pk_fma_f32 v[234:235], v[156:157], v[208:209], v[234:235]
	v_pk_fma_f32 v[232:233], v[154:155], v[206:207], v[232:233]
	global_store_dwordx4 v[218:219], v[232:235], off offset:512
	ds_bpermute_b32 v172, v211, v12
	ds_bpermute_b32 v176, v211, v8
	ds_bpermute_b32 v173, v211, v13
	ds_bpermute_b32 v177, v211, v9
	ds_bpermute_b32 v174, v211, v14
	ds_bpermute_b32 v178, v211, v10
	ds_bpermute_b32 v175, v211, v15
	ds_bpermute_b32 v179, v211, v11
	s_waitcnt lgkmcnt(8)
	s_waitcnt vmcnt(4)
	v_lshl_add_u64 v[216:217], v[216:217], 0, s[50:51]
	v_lshl_add_u64 v[218:219], v[218:219], 0, s[50:51]
	v_cndmask_b32_e64 v154, v140, v144, s[10:11]
	v_cndmask_b32_e64 v155, v141, v145, s[10:11]
	v_cndmask_b32_e64 v156, v142, v146, s[10:11]
	v_cndmask_b32_e64 v157, v143, v147, s[10:11]
	v_pk_fma_f32 v[238:239], v[156:157], v[204:205], v[238:239]
	v_pk_fma_f32 v[236:237], v[154:155], v[202:203], v[236:237]
	global_store_dwordx4 v[216:217], v[236:239], off
	ds_bpermute_b32 v140, v210, v4
	ds_bpermute_b32 v144, v210, v0
	ds_bpermute_b32 v141, v210, v5
	ds_bpermute_b32 v145, v210, v1
	ds_bpermute_b32 v142, v210, v6
	ds_bpermute_b32 v146, v210, v2
	ds_bpermute_b32 v143, v210, v7
	ds_bpermute_b32 v147, v210, v3
	s_waitcnt lgkmcnt(8)
	v_cndmask_b32_e64 v154, v172, v176, s[10:11]
	v_cndmask_b32_e64 v155, v173, v177, s[10:11]
	v_cndmask_b32_e64 v156, v174, v178, s[10:11]
	v_cndmask_b32_e64 v157, v175, v179, s[10:11]
	v_pk_fma_f32 v[242:243], v[156:157], v[204:205], v[242:243]
	v_pk_fma_f32 v[240:241], v[154:155], v[202:203], v[240:241]
	global_store_dwordx4 v[218:219], v[240:243], off
	ds_bpermute_b32 v172, v211, v4
	ds_bpermute_b32 v176, v211, v0
	ds_bpermute_b32 v173, v211, v5
	ds_bpermute_b32 v177, v211, v1
	ds_bpermute_b32 v174, v211, v6
	ds_bpermute_b32 v178, v211, v2
	ds_bpermute_b32 v175, v211, v7
	ds_bpermute_b32 v179, v211, v3
	s_waitcnt lgkmcnt(8)
	v_cndmask_b32_e64 v154, v140, v144, s[10:11]
	v_cndmask_b32_e64 v155, v141, v145, s[10:11]
	v_cndmask_b32_e64 v156, v142, v146, s[10:11]
	v_cndmask_b32_e64 v157, v143, v147, s[10:11]
	v_pk_fma_f32 v[246:247], v[156:157], v[208:209], v[246:247]
	v_pk_fma_f32 v[244:245], v[154:155], v[206:207], v[244:245]
	global_store_dwordx4 v[216:217], v[244:247], off offset:512
	s_waitcnt lgkmcnt(0)
	v_cndmask_b32_e64 v154, v172, v176, s[10:11]
	v_cndmask_b32_e64 v155, v173, v177, s[10:11]
	v_cndmask_b32_e64 v156, v174, v178, s[10:11]
	v_cndmask_b32_e64 v157, v175, v179, s[10:11]
	v_pk_fma_f32 v[250:251], v[156:157], v[208:209], v[250:251]
	v_pk_fma_f32 v[248:249], v[154:155], v[206:207], v[248:249]
	global_store_dwordx4 v[218:219], v[248:251], off offset:512
	s_mov_b64 s[4:5], -1
	s_andn2_b64 vcc, exec, s[2:3]
	s_cbranch_vccnz .LBB0_1128
	s_andn2_b64 vcc, exec, s[16:17]
	s_cbranch_vccnz .LBB0_1127
	s_barrier
	s_branch .LBB0_1127

;   DI void operator()(const pg8::f32x4 (&acc)[2][2][4][2], const pg8::Unit& u, int wr, int wc, int fr, int fq) const {
;     const int row0 = u.pm * 256 + wr * 64 + fr, col0 = u.pn * 256 + wc * 32 + 8 * fq;
;     const int b = (u.pm * 256) / TT;
; #pragma unroll
;     for (int ai = 0; ai < 2; ++ai)
; #pragma unroll
;       for (int m = 0; m < 4; ++m) {
;         const int row = row0 + ai * 128 + m * 16;
;         const int t = row - b * TT;
;         const bool isc = t >= TL;
;         float* dst = isc ? xc + ((size_t)b * TC + (t - TL)) * DM : xout + ((size_t)b * TL + t) * DM;
;         const float* src = src_input ? (isc ? cin + ((size_t)b * TC + (t - TL)) * DM : xin + ((size_t)b * TL + t) * DM) : dst;
;         const float* gate = modl + (size_t)(isc ? 16 : b) * 6144 + gi * DM;
; #pragma unroll
;         for (int bj = 0; bj < 2; ++bj) {
;           const int col = col0 + bj * 128;
; #pragma unroll
;           for (int n = 0; n < 2; ++n) {
;             pg8::f32x4 sv = *(const pg8::f32x4*)(src + col + 4 * n);
;             pg8::f32x4 gv = *(const pg8::f32x4*)(gate + col + 4 * n);
;             pg8::f32x4 o = sv + gv * acc[ai][bj][m][n];
;             *(pg8::f32x4*)(dst + col + 4 * n) = o;
;           }
;         }
;       }
;   }
.LBB0_1507:
	s_mov_b32 s4, 0x38e38e39
	v_mul_hi_i32 v142, v148, s4
	v_lshrrev_b32_e32 v144, 31, v142
	v_ashrrev_i32_e32 v142, 1, v142
	v_add_u32_e32 v142, v142, v144
	s_movk_i32 s4, 0xf700
	s_load_dwordx4 s[24:27], s[0:1], 0x100
	v_lshlrev_b32_e32 v143, 8, v148
	v_mul_lo_u32 v144, v142, s4
	v_add_u32_e32 v143, v144, v143
	v_add_u32_e32 v160, v143, v154
	v_ashrrev_i32_e32 v143, 31, v142
	v_readlane_b32 s4, v252, 14
	s_movk_i32 s21, 0x7ff
	v_lshlrev_b64 v[144:145], 23, v[142:143]
	v_lshlrev_b64 v[146:147], 20, v[142:143]
	v_ashrrev_i32_e32 v143, 31, v160
	v_add_u32_e32 v148, 0xfffff800, v160
	v_readlane_b32 s5, v252, 15
	v_cmp_lt_i32_e32 vcc, s21, v160
	v_lshl_or_b32 v150, v149, 8, v156
	s_waitcnt lgkmcnt(0)
	v_lshl_add_u64 v[144:145], s[24:25], 0, v[144:145]
	v_lshl_add_u64 v[146:147], s[4:5], 0, v[146:147]
	v_cndmask_b32_e64 v149, v143, 0, vcc
	v_cndmask_b32_e32 v148, v160, v148, vcc
	v_cndmask_b32_e32 v163, v145, v147, vcc
	v_cndmask_b32_e32 v162, v144, v146, vcc
	v_lshlrev_b64 v[148:149], 12, v[148:149]
	v_lshl_add_u64 v[162:163], v[162:163], 0, v[148:149]
	v_cndmask_b32_e64 v143, v142, 16, vcc
	v_mov_b64_e32 v[148:149], s[10:11]
	s_movk_i32 s22, 0x6000
	v_ashrrev_i32_e32 v151, 31, v150
	v_mad_i64_i32 v[164:165], s[4:5], v143, s22, v[148:149]
	v_lshlrev_b64 v[150:151], 2, v[150:151]
	v_lshl_add_u64 v[176:177], v[164:165], 0, v[150:151]
	v_lshl_add_u64 v[174:175], v[162:163], 0, v[150:151]
	s_mov_b32 s4, 0xaaaaaaaa
	s_mov_b32 s5, 0xaaaaaaaa
	s_mov_b64 s[24:25], 0x10000
	s_mov_b64 s[26:27], 0x50000
	v_and_b32_e32 v166, 63, v182
	v_lshrrev_b32_e32 v167, 3, v166
	v_and_b32_e32 v168, 7, v166
	v_lshrrev_b32_e32 v210, 1, v168
	v_lshl_add_u32 v210, v210, 4, v167
	v_lshlrev_b32_e32 v210, 2, v210
	v_add_u32_e32 v211, 32, v210
	v_lshrrev_b32_e32 v169, 4, v166
	v_and_b32_e32 v170, 15, v166
	v_lshlrev_b32_e32 v171, 4, v168
	v_lshlrev_b32_e32 v169, 5, v169
	v_sub_u32_e32 v171, v171, v169
	v_sub_u32_e32 v172, v167, v170
	v_lshl_add_u32 v172, v172, 12, v171
	v_ashrrev_i32_e32 v173, 31, v172
	v_ashrrev_i32_e32 v170, 31, v171
	v_add_co_u32_e32 v212, vcc, v174, v172
	s_nop 1
	v_addc_co_u32_e32 v213, vcc, v175, v173, vcc
	v_lshl_add_u64 v[214:215], v[212:213], 0, s[24:25]
	v_add_co_u32_e32 v214, vcc, 0xffff8000, v214
	s_nop 1
	v_addc_co_u32_e32 v215, vcc, -1, v215, vcc
	v_mov_b32_e32 v150, v212
	v_mov_b32_e32 v151, v213
	v_mov_b32_e32 v192, v214
	v_mov_b32_e32 v193, v215
	v_add_co_u32_e32 v176, vcc, v176, v171
	s_nop 1
	v_addc_co_u32_e32 v177, vcc, v177, v170, vcc
	global_load_dwordx4 v[202:205], v[176:177], off
	global_load_dwordx4 v[206:209], v[176:177], off offset:512
	global_load_dwordx4 v[216:219], v[212:213], off
	global_load_dwordx4 v[220:223], v[214:215], off
	global_load_dwordx4 v[224:227], v[212:213], off offset:512
	global_load_dwordx4 v[228:231], v[214:215], off offset:512
	v_lshl_add_u64 v[212:213], v[212:213], 0, s[24:25]
	v_lshl_add_u64 v[214:215], v[214:215], 0, s[24:25]
	global_load_dwordx4 v[232:235], v[212:213], off
	global_load_dwordx4 v[236:239], v[214:215], off
	global_load_dwordx4 v[240:243], v[212:213], off offset:512
	global_load_dwordx4 v[244:247], v[214:215], off offset:512
	ds_bpermute_b32 v142, v210, v124
	ds_bpermute_b32 v146, v210, v120
	ds_bpermute_b32 v143, v210, v125
	ds_bpermute_b32 v147, v210, v121
	ds_bpermute_b32 v144, v210, v126
	ds_bpermute_b32 v148, v210, v122
	ds_bpermute_b32 v145, v210, v127
	ds_bpermute_b32 v149, v210, v123
	ds_bpermute_b32 v178, v211, v124
	ds_bpermute_b32 v248, v211, v120
	ds_bpermute_b32 v179, v211, v125
	ds_bpermute_b32 v249, v211, v121
	ds_bpermute_b32 v180, v211, v126
	ds_bpermute_b32 v194, v211, v122
	ds_bpermute_b32 v181, v211, v127
	ds_bpermute_b32 v195, v211, v123
	s_waitcnt lgkmcnt(8)
	s_waitcnt vmcnt(4)
	v_cndmask_b32_e64 v162, v142, v146, s[4:5]
	v_cndmask_b32_e64 v163, v143, v147, s[4:5]
	v_cndmask_b32_e64 v164, v144, v148, s[4:5]
	v_cndmask_b32_e64 v165, v145, v149, s[4:5]
	v_pk_fma_f32 v[218:219], v[164:165], v[204:205], v[218:219]
	v_pk_fma_f32 v[216:217], v[162:163], v[202:203], v[216:217]
	global_store_dwordx4 v[150:151], v[216:219], off
	ds_bpermute_b32 v142, v210, v116
	ds_bpermute_b32 v146, v210, v104
	ds_bpermute_b32 v143, v210, v117
	ds_bpermute_b32 v147, v210, v105
	ds_bpermute_b32 v144, v210, v118
	ds_bpermute_b32 v148, v210, v106
	ds_bpermute_b32 v145, v210, v119
	ds_bpermute_b32 v149, v210, v107
	s_waitcnt lgkmcnt(8)
	v_cndmask_b32_e64 v162, v178, v248, s[4:5]
	v_cndmask_b32_e64 v163, v179, v249, s[4:5]
	v_cndmask_b32_e64 v164, v180, v194, s[4:5]
	v_cndmask_b32_e64 v165, v181, v195, s[4:5]
	v_pk_fma_f32 v[222:223], v[164:165], v[204:205], v[222:223]
	v_pk_fma_f32 v[220:221], v[162:163], v[202:203], v[220:221]
	global_store_dwordx4 v[192:193], v[220:223], off
	ds_bpermute_b32 v178, v211, v116
	ds_bpermute_b32 v248, v211, v104
	ds_bpermute_b32 v179, v211, v117
	ds_bpermute_b32 v249, v211, v105
	ds_bpermute_b32 v180, v211, v118
	ds_bpermute_b32 v194, v211, v106
	ds_bpermute_b32 v181, v211, v119
	ds_bpermute_b32 v195, v211, v107
	s_waitcnt lgkmcnt(8)
	v_cndmask_b32_e64 v162, v142, v146, s[4:5]
	v_cndmask_b32_e64 v163, v143, v147, s[4:5]
	v_cndmask_b32_e64 v164, v144, v148, s[4:5]
	v_cndmask_b32_e64 v165, v145, v149, s[4:5]
	v_pk_fma_f32 v[226:227], v[164:165], v[208:209], v[226:227]
	v_pk_fma_f32 v[224:225], v[162:163], v[206:207], v[224:225]
	global_store_dwordx4 v[150:151], v[224:227], off offset:512
	ds_bpermute_b32 v142, v210, v112
	ds_bpermute_b32 v146, v210, v108
	ds_bpermute_b32 v143, v210, v113
	ds_bpermute_b32 v147, v210, v109
	ds_bpermute_b32 v144, v210, v114
	ds_bpermute_b32 v148, v210, v110
	ds_bpermute_b32 v145, v210, v115
	ds_bpermute_b32 v149, v210, v111
	s_waitcnt lgkmcnt(8)
;   DI void operator()(const pg8::f32x4 (&acc)[2][2][4][2], const pg8::Unit& u, int wr, int wc, int fr, int fq) const {
;     const int row0 = u.pm * 256 + wr * 64 + fr, col0 = u.pn * 256 + wc * 32 + 8 * fq;
;     const int b = (u.pm * 256) / TT;
; #pragma unroll
;     for (int ai = 0; ai < 2; ++ai)
; #pragma unroll
;       for (int m = 0; m < 4; ++m) {
;         const int row = row0 + ai * 128 + m * 16;
;         const int t = row - b * TT;
;         const bool isc = t >= TL;
;         float* dst = isc ? xc + ((size_t)b * TC + (t - TL)) * DM : xout + ((size_t)b * TL + t) * DM;
;         const float* src = src_input ? (isc ? cin + ((size_t)b * TC + (t - TL)) * DM : xin + ((size_t)b * TL + t) * DM) : dst;
;         const float* gate = modl + (size_t)(isc ? 16 : b) * 6144 + gi * DM;
; #pragma unroll
;         for (int bj = 0; bj < 2; ++bj) {
;           const int col = col0 + bj * 128;
; #pragma unroll
;           for (int n = 0; n < 2; ++n) {
;             pg8::f32x4 sv = *(const pg8::f32x4*)(src + col + 4 * n);
;             pg8::f32x4 gv = *(const pg8::f32x4*)(gate + col + 4 * n);
;             pg8::f32x4 o = sv + gv * acc[ai][bj][m][n];
;             *(pg8::f32x4*)(dst + col + 4 * n) = o;
;           }
;         }
;       }
;   }
	v_cndmask_b32_e64 v162, v178, v248, s[4:5]
	v_cndmask_b32_e64 v163, v179, v249, s[4:5]
	v_cndmask_b32_e64 v164, v180, v194, s[4:5]
	v_cndmask_b32_e64 v165, v181, v195, s[4:5]
	v_pk_fma_f32 v[230:231], v[164:165], v[208:209], v[230:231]
	v_pk_fma_f32 v[228:229], v[162:163], v[206:207], v[228:229]
	global_store_dwordx4 v[192:193], v[228:231], off offset:512
	v_lshl_add_u64 v[212:213], v[212:213], 0, s[24:25]
	v_lshl_add_u64 v[214:215], v[214:215], 0, s[24:25]
	global_load_dwordx4 v[216:219], v[212:213], off
	global_load_dwordx4 v[220:223], v[214:215], off
	global_load_dwordx4 v[224:227], v[212:213], off offset:512
	global_load_dwordx4 v[228:231], v[214:215], off offset:512
	ds_bpermute_b32 v178, v211, v112
	ds_bpermute_b32 v248, v211, v108
	ds_bpermute_b32 v179, v211, v113
	ds_bpermute_b32 v249, v211, v109
	ds_bpermute_b32 v180, v211, v114
	ds_bpermute_b32 v194, v211, v110
	ds_bpermute_b32 v181, v211, v115
	ds_bpermute_b32 v195, v211, v111
	s_waitcnt lgkmcnt(8)
	s_waitcnt vmcnt(8)
	v_lshl_add_u64 v[150:151], v[150:151], 0, s[24:25]
	v_lshl_add_u64 v[192:193], v[192:193], 0, s[24:25]
	v_cndmask_b32_e64 v162, v142, v146, s[4:5]
	v_cndmask_b32_e64 v163, v143, v147, s[4:5]
	v_cndmask_b32_e64 v164, v144, v148, s[4:5]
	v_cndmask_b32_e64 v165, v145, v149, s[4:5]
	v_pk_fma_f32 v[234:235], v[164:165], v[204:205], v[234:235]
	v_pk_fma_f32 v[232:233], v[162:163], v[202:203], v[232:233]
	global_store_dwordx4 v[150:151], v[232:235], off
	ds_bpermute_b32 v142, v210, v100
	ds_bpermute_b32 v146, v210, v88
	ds_bpermute_b32 v143, v210, v101
	ds_bpermute_b32 v147, v210, v89
	ds_bpermute_b32 v144, v210, v102
	ds_bpermute_b32 v148, v210, v90
	ds_bpermute_b32 v145, v210, v103
	ds_bpermute_b32 v149, v210, v91
	s_waitcnt lgkmcnt(8)
	v_cndmask_b32_e64 v162, v178, v248, s[4:5]
	v_cndmask_b32_e64 v163, v179, v249, s[4:5]
	v_cndmask_b32_e64 v164, v180, v194, s[4:5]
	v_cndmask_b32_e64 v165, v181, v195, s[4:5]
	v_pk_fma_f32 v[238:239], v[164:165], v[204:205], v[238:239]
	v_pk_fma_f32 v[236:237], v[162:163], v[202:203], v[236:237]
	global_store_dwordx4 v[192:193], v[236:239], off
	ds_bpermute_b32 v178, v211, v100
	ds_bpermute_b32 v248, v211, v88
	ds_bpermute_b32 v179, v211, v101
	ds_bpermute_b32 v249, v211, v89
	ds_bpermute_b32 v180, v211, v102
	ds_bpermute_b32 v194, v211, v90
	ds_bpermute_b32 v181, v211, v103
	ds_bpermute_b32 v195, v211, v91
	s_waitcnt lgkmcnt(8)
	v_cndmask_b32_e64 v162, v142, v146, s[4:5]
	v_cndmask_b32_e64 v163, v143, v147, s[4:5]
	v_cndmask_b32_e64 v164, v144, v148, s[4:5]
	v_cndmask_b32_e64 v165, v145, v149, s[4:5]
	v_pk_fma_f32 v[242:243], v[164:165], v[208:209], v[242:243]
	v_pk_fma_f32 v[240:241], v[162:163], v[206:207], v[240:241]
	global_store_dwordx4 v[150:151], v[240:243], off offset:512
	ds_bpermute_b32 v142, v210, v96
	ds_bpermute_b32 v146, v210, v92
	ds_bpermute_b32 v143, v210, v97
	ds_bpermute_b32 v147, v210, v93
	ds_bpermute_b32 v144, v210, v98
	ds_bpermute_b32 v148, v210, v94
	ds_bpermute_b32 v145, v210, v99
	ds_bpermute_b32 v149, v210, v95
	s_waitcnt lgkmcnt(8)
	v_cndmask_b32_e64 v162, v178, v248, s[4:5]
	v_cndmask_b32_e64 v163, v179, v249, s[4:5]
	v_cndmask_b32_e64 v164, v180, v194, s[4:5]
	v_cndmask_b32_e64 v165, v181, v195, s[4:5]
	v_pk_fma_f32 v[246:247], v[164:165], v[208:209], v[246:247]
	v_pk_fma_f32 v[244:245], v[162:163], v[206:207], v[244:245]
	global_store_dwordx4 v[192:193], v[244:247], off offset:512
	v_lshl_add_u64 v[212:213], v[212:213], 0, s[24:25]
	v_lshl_add_u64 v[214:215], v[214:215], 0, s[24:25]
	global_load_dwordx4 v[232:235], v[212:213], off
	global_load_dwordx4 v[236:239], v[214:215], off
	global_load_dwordx4 v[240:243], v[212:213], off offset:512
	global_load_dwordx4 v[244:247], v[214:215], off offset:512
	ds_bpermute_b32 v178, v211, v96
	ds_bpermute_b32 v248, v211, v92
	ds_bpermute_b32 v179, v211, v97
	ds_bpermute_b32 v249, v211, v93
	ds_bpermute_b32 v180, v211, v98
	ds_bpermute_b32 v194, v211, v94
	ds_bpermute_b32 v181, v211, v99
	ds_bpermute_b32 v195, v211, v95
	s_waitcnt lgkmcnt(8)
	s_waitcnt vmcnt(8)
	v_lshl_add_u64 v[150:151], v[150:151], 0, s[24:25]
	v_lshl_add_u64 v[192:193], v[192:193], 0, s[24:25]
	v_cndmask_b32_e64 v162, v142, v146, s[4:5]
	v_cndmask_b32_e64 v163, v143, v147, s[4:5]
	v_cndmask_b32_e64 v164, v144, v148, s[4:5]
	v_cndmask_b32_e64 v165, v145, v149, s[4:5]
	v_pk_fma_f32 v[218:219], v[164:165], v[204:205], v[218:219]
	v_pk_fma_f32 v[216:217], v[162:163], v[202:203], v[216:217]
	global_store_dwordx4 v[150:151], v[216:219], off
	ds_bpermute_b32 v142, v210, v84
	ds_bpermute_b32 v146, v210, v72
	ds_bpermute_b32 v143, v210, v85
	ds_bpermute_b32 v147, v210, v73
	ds_bpermute_b32 v144, v210, v86
	ds_bpermute_b32 v148, v210, v74
	ds_bpermute_b32 v145, v210, v87
	ds_bpermute_b32 v149, v210, v75
	s_waitcnt lgkmcnt(8)
	v_cndmask_b32_e64 v162, v178, v248, s[4:5]
	v_cndmask_b32_e64 v163, v179, v249, s[4:5]
	v_cndmask_b32_e64 v164, v180, v194, s[4:5]
	v_cndmask_b32_e64 v165, v181, v195, s[4:5]
	v_pk_fma_f32 v[222:223], v[164:165], v[204:205], v[222:223]
	v_pk_fma_f32 v[220:221], v[162:163], v[202:203], v[220:221]
	global_store_dwordx4 v[192:193], v[220:223], off
	ds_bpermute_b32 v178, v211, v84
	ds_bpermute_b32 v248, v211, v72
	ds_bpermute_b32 v179, v211, v85
	ds_bpermute_b32 v249, v211, v73
	ds_bpermute_b32 v180, v211, v86
	ds_bpermute_b32 v194, v211, v74
	ds_bpermute_b32 v181, v211, v87
	ds_bpermute_b32 v195, v211, v75
	s_waitcnt lgkmcnt(8)
;   DI void operator()(const pg8::f32x4 (&acc)[2][2][4][2], const pg8::Unit& u, int wr, int wc, int fr, int fq) const {
;     const int row0 = u.pm * 256 + wr * 64 + fr, col0 = u.pn * 256 + wc * 32 + 8 * fq;
;     const int b = (u.pm * 256) / TT;
; #pragma unroll
;     for (int ai = 0; ai < 2; ++ai)
; #pragma unroll
;       for (int m = 0; m < 4; ++m) {
;         const int row = row0 + ai * 128 + m * 16;
;         const int t = row - b * TT;
;         const bool isc = t >= TL;
;         float* dst = isc ? xc + ((size_t)b * TC + (t - TL)) * DM : xout + ((size_t)b * TL + t) * DM;
;         const float* src = src_input ? (isc ? cin + ((size_t)b * TC + (t - TL)) * DM : xin + ((size_t)b * TL + t) * DM) : dst;
;         const float* gate = modl + (size_t)(isc ? 16 : b) * 6144 + gi * DM;
; #pragma unroll
;         for (int bj = 0; bj < 2; ++bj) {
;           const int col = col0 + bj * 128;
; #pragma unroll
;           for (int n = 0; n < 2; ++n) {
;             pg8::f32x4 sv = *(const pg8::f32x4*)(src + col + 4 * n);
;             pg8::f32x4 gv = *(const pg8::f32x4*)(gate + col + 4 * n);
;             pg8::f32x4 o = sv + gv * acc[ai][bj][m][n];
;             *(pg8::f32x4*)(dst + col + 4 * n) = o;
;           }
;         }
;       }
;   }
	v_cndmask_b32_e64 v162, v142, v146, s[4:5]
	v_cndmask_b32_e64 v163, v143, v147, s[4:5]
	v_cndmask_b32_e64 v164, v144, v148, s[4:5]
	v_cndmask_b32_e64 v165, v145, v149, s[4:5]
	v_pk_fma_f32 v[226:227], v[164:165], v[208:209], v[226:227]
	v_pk_fma_f32 v[224:225], v[162:163], v[206:207], v[224:225]
	global_store_dwordx4 v[150:151], v[224:227], off offset:512
	ds_bpermute_b32 v142, v210, v80
	ds_bpermute_b32 v146, v210, v76
	ds_bpermute_b32 v143, v210, v81
	ds_bpermute_b32 v147, v210, v77
	ds_bpermute_b32 v144, v210, v82
	ds_bpermute_b32 v148, v210, v78
	ds_bpermute_b32 v145, v210, v83
	ds_bpermute_b32 v149, v210, v79
	s_waitcnt lgkmcnt(8)
	v_cndmask_b32_e64 v162, v178, v248, s[4:5]
	v_cndmask_b32_e64 v163, v179, v249, s[4:5]
	v_cndmask_b32_e64 v164, v180, v194, s[4:5]
	v_cndmask_b32_e64 v165, v181, v195, s[4:5]
	v_pk_fma_f32 v[230:231], v[164:165], v[208:209], v[230:231]
	v_pk_fma_f32 v[228:229], v[162:163], v[206:207], v[228:229]
	global_store_dwordx4 v[192:193], v[228:231], off offset:512
	v_lshl_add_u64 v[212:213], v[212:213], 0, s[26:27]
	v_lshl_add_u64 v[214:215], v[214:215], 0, s[26:27]
	global_load_dwordx4 v[216:219], v[212:213], off
	global_load_dwordx4 v[220:223], v[214:215], off
	global_load_dwordx4 v[224:227], v[212:213], off offset:512
	global_load_dwordx4 v[228:231], v[214:215], off offset:512
	ds_bpermute_b32 v178, v211, v80
	ds_bpermute_b32 v248, v211, v76
	ds_bpermute_b32 v179, v211, v81
	ds_bpermute_b32 v249, v211, v77
	ds_bpermute_b32 v180, v211, v82
	ds_bpermute_b32 v194, v211, v78
	ds_bpermute_b32 v181, v211, v83
	ds_bpermute_b32 v195, v211, v79
	s_waitcnt lgkmcnt(8)
	s_waitcnt vmcnt(8)
	v_lshl_add_u64 v[150:151], v[150:151], 0, s[24:25]
	v_lshl_add_u64 v[192:193], v[192:193], 0, s[24:25]
	v_cndmask_b32_e64 v162, v142, v146, s[4:5]
	v_cndmask_b32_e64 v163, v143, v147, s[4:5]
	v_cndmask_b32_e64 v164, v144, v148, s[4:5]
	v_cndmask_b32_e64 v165, v145, v149, s[4:5]
	v_pk_fma_f32 v[234:235], v[164:165], v[204:205], v[234:235]
	v_pk_fma_f32 v[232:233], v[162:163], v[202:203], v[232:233]
	global_store_dwordx4 v[150:151], v[232:235], off
	ds_bpermute_b32 v142, v210, v68
	ds_bpermute_b32 v146, v210, v64
	ds_bpermute_b32 v143, v210, v69
	ds_bpermute_b32 v147, v210, v65
	ds_bpermute_b32 v144, v210, v70
	ds_bpermute_b32 v148, v210, v66
	ds_bpermute_b32 v145, v210, v71
	ds_bpermute_b32 v149, v210, v67
	s_waitcnt lgkmcnt(8)
	v_cndmask_b32_e64 v162, v178, v248, s[4:5]
	v_cndmask_b32_e64 v163, v179, v249, s[4:5]
	v_cndmask_b32_e64 v164, v180, v194, s[4:5]
	v_cndmask_b32_e64 v165, v181, v195, s[4:5]
	v_pk_fma_f32 v[238:239], v[164:165], v[204:205], v[238:239]
	v_pk_fma_f32 v[236:237], v[162:163], v[202:203], v[236:237]
	global_store_dwordx4 v[192:193], v[236:239], off
	ds_bpermute_b32 v178, v211, v68
	ds_bpermute_b32 v248, v211, v64
	ds_bpermute_b32 v179, v211, v69
	ds_bpermute_b32 v249, v211, v65
	ds_bpermute_b32 v180, v211, v70
	ds_bpermute_b32 v194, v211, v66
	ds_bpermute_b32 v181, v211, v71
	ds_bpermute_b32 v195, v211, v67
	s_waitcnt lgkmcnt(8)
	v_cndmask_b32_e64 v162, v142, v146, s[4:5]
	v_cndmask_b32_e64 v163, v143, v147, s[4:5]
	v_cndmask_b32_e64 v164, v144, v148, s[4:5]
	v_cndmask_b32_e64 v165, v145, v149, s[4:5]
	v_pk_fma_f32 v[242:243], v[164:165], v[208:209], v[242:243]
	v_pk_fma_f32 v[240:241], v[162:163], v[206:207], v[240:241]
	global_store_dwordx4 v[150:151], v[240:243], off offset:512
	ds_bpermute_b32 v142, v210, v60
	ds_bpermute_b32 v146, v210, v56
	ds_bpermute_b32 v143, v210, v61
	ds_bpermute_b32 v147, v210, v57
	ds_bpermute_b32 v144, v210, v62
	ds_bpermute_b32 v148, v210, v58
	ds_bpermute_b32 v145, v210, v63
	ds_bpermute_b32 v149, v210, v59
	s_waitcnt lgkmcnt(8)
	v_cndmask_b32_e64 v162, v178, v248, s[4:5]
	v_cndmask_b32_e64 v163, v179, v249, s[4:5]
	v_cndmask_b32_e64 v164, v180, v194, s[4:5]
	v_cndmask_b32_e64 v165, v181, v195, s[4:5]
	v_pk_fma_f32 v[246:247], v[164:165], v[208:209], v[246:247]
	v_pk_fma_f32 v[244:245], v[162:163], v[206:207], v[244:245]
	global_store_dwordx4 v[192:193], v[244:247], off offset:512
	v_lshl_add_u64 v[212:213], v[212:213], 0, s[24:25]
	v_lshl_add_u64 v[214:215], v[214:215], 0, s[24:25]
	global_load_dwordx4 v[232:235], v[212:213], off
	global_load_dwordx4 v[236:239], v[214:215], off
	global_load_dwordx4 v[240:243], v[212:213], off offset:512
	global_load_dwordx4 v[244:247], v[214:215], off offset:512
	ds_bpermute_b32 v178, v211, v60
	ds_bpermute_b32 v248, v211, v56
	ds_bpermute_b32 v179, v211, v61
	ds_bpermute_b32 v249, v211, v57
	ds_bpermute_b32 v180, v211, v62
	ds_bpermute_b32 v194, v211, v58
	ds_bpermute_b32 v181, v211, v63
	ds_bpermute_b32 v195, v211, v59
	s_waitcnt lgkmcnt(8)
	s_waitcnt vmcnt(8)
	v_lshl_add_u64 v[150:151], v[150:151], 0, s[26:27]
	v_lshl_add_u64 v[192:193], v[192:193], 0, s[26:27]
	v_cndmask_b32_e64 v162, v142, v146, s[4:5]
	v_cndmask_b32_e64 v163, v143, v147, s[4:5]
	v_cndmask_b32_e64 v164, v144, v148, s[4:5]
	v_cndmask_b32_e64 v165, v145, v149, s[4:5]
	v_pk_fma_f32 v[218:219], v[164:165], v[204:205], v[218:219]
	v_pk_fma_f32 v[216:217], v[162:163], v[202:203], v[216:217]
	global_store_dwordx4 v[150:151], v[216:219], off
	ds_bpermute_b32 v142, v210, v52
	ds_bpermute_b32 v146, v210, v40
	ds_bpermute_b32 v143, v210, v53
	ds_bpermute_b32 v147, v210, v41
	ds_bpermute_b32 v144, v210, v54
	ds_bpermute_b32 v148, v210, v42
	ds_bpermute_b32 v145, v210, v55
	ds_bpermute_b32 v149, v210, v43
	s_waitcnt lgkmcnt(8)
;   DI void operator()(const pg8::f32x4 (&acc)[2][2][4][2], const pg8::Unit& u, int wr, int wc, int fr, int fq) const {
;     const int row0 = u.pm * 256 + wr * 64 + fr, col0 = u.pn * 256 + wc * 32 + 8 * fq;
;     const int b = (u.pm * 256) / TT;
; #pragma unroll
;     for (int ai = 0; ai < 2; ++ai)
; #pragma unroll
;       for (int m = 0; m < 4; ++m) {
;         const int row = row0 + ai * 128 + m * 16;
;         const int t = row - b * TT;
;         const bool isc = t >= TL;
;         float* dst = isc ? xc + ((size_t)b * TC + (t - TL)) * DM : xout + ((size_t)b * TL + t) * DM;
;         const float* src = src_input ? (isc ? cin + ((size_t)b * TC + (t - TL)) * DM : xin + ((size_t)b * TL + t) * DM) : dst;
;         const float* gate = modl + (size_t)(isc ? 16 : b) * 6144 + gi * DM;
; #pragma unroll
;         for (int bj = 0; bj < 2; ++bj) {
;           const int col = col0 + bj * 128;
; #pragma unroll
;           for (int n = 0; n < 2; ++n) {
;             pg8::f32x4 sv = *(const pg8::f32x4*)(src + col + 4 * n);
;             pg8::f32x4 gv = *(const pg8::f32x4*)(gate + col + 4 * n);
;             pg8::f32x4 o = sv + gv * acc[ai][bj][m][n];
;             *(pg8::f32x4*)(dst + col + 4 * n) = o;
;           }
;         }
;       }
;   }
	v_cndmask_b32_e64 v162, v178, v248, s[4:5]
	v_cndmask_b32_e64 v163, v179, v249, s[4:5]
	v_cndmask_b32_e64 v164, v180, v194, s[4:5]
	v_cndmask_b32_e64 v165, v181, v195, s[4:5]
	v_pk_fma_f32 v[222:223], v[164:165], v[204:205], v[222:223]
	v_pk_fma_f32 v[220:221], v[162:163], v[202:203], v[220:221]
	global_store_dwordx4 v[192:193], v[220:223], off
	ds_bpermute_b32 v178, v211, v52
	ds_bpermute_b32 v248, v211, v40
	ds_bpermute_b32 v179, v211, v53
	ds_bpermute_b32 v249, v211, v41
	ds_bpermute_b32 v180, v211, v54
	ds_bpermute_b32 v194, v211, v42
	ds_bpermute_b32 v181, v211, v55
	ds_bpermute_b32 v195, v211, v43
	s_waitcnt lgkmcnt(8)
	v_cndmask_b32_e64 v162, v142, v146, s[4:5]
	v_cndmask_b32_e64 v163, v143, v147, s[4:5]
	v_cndmask_b32_e64 v164, v144, v148, s[4:5]
	v_cndmask_b32_e64 v165, v145, v149, s[4:5]
	v_pk_fma_f32 v[226:227], v[164:165], v[208:209], v[226:227]
	v_pk_fma_f32 v[224:225], v[162:163], v[206:207], v[224:225]
	global_store_dwordx4 v[150:151], v[224:227], off offset:512
	ds_bpermute_b32 v142, v210, v48
	ds_bpermute_b32 v146, v210, v44
	ds_bpermute_b32 v143, v210, v49
	ds_bpermute_b32 v147, v210, v45
	ds_bpermute_b32 v144, v210, v50
	ds_bpermute_b32 v148, v210, v46
	ds_bpermute_b32 v145, v210, v51
	ds_bpermute_b32 v149, v210, v47
	s_waitcnt lgkmcnt(8)
	v_cndmask_b32_e64 v162, v178, v248, s[4:5]
	v_cndmask_b32_e64 v163, v179, v249, s[4:5]
	v_cndmask_b32_e64 v164, v180, v194, s[4:5]
	v_cndmask_b32_e64 v165, v181, v195, s[4:5]
	v_pk_fma_f32 v[230:231], v[164:165], v[208:209], v[230:231]
	v_pk_fma_f32 v[228:229], v[162:163], v[206:207], v[228:229]
	global_store_dwordx4 v[192:193], v[228:231], off offset:512
	v_lshl_add_u64 v[212:213], v[212:213], 0, s[24:25]
	v_lshl_add_u64 v[214:215], v[214:215], 0, s[24:25]
	global_load_dwordx4 v[216:219], v[212:213], off
	global_load_dwordx4 v[220:223], v[214:215], off
	global_load_dwordx4 v[224:227], v[212:213], off offset:512
	global_load_dwordx4 v[228:231], v[214:215], off offset:512
	ds_bpermute_b32 v178, v211, v48
	ds_bpermute_b32 v248, v211, v44
	ds_bpermute_b32 v179, v211, v49
	ds_bpermute_b32 v249, v211, v45
	ds_bpermute_b32 v180, v211, v50
	ds_bpermute_b32 v194, v211, v46
	ds_bpermute_b32 v181, v211, v51
	ds_bpermute_b32 v195, v211, v47
	s_waitcnt lgkmcnt(8)
	s_waitcnt vmcnt(8)
	v_lshl_add_u64 v[150:151], v[150:151], 0, s[24:25]
	v_lshl_add_u64 v[192:193], v[192:193], 0, s[24:25]
	v_cndmask_b32_e64 v162, v142, v146, s[4:5]
	v_cndmask_b32_e64 v163, v143, v147, s[4:5]
	v_cndmask_b32_e64 v164, v144, v148, s[4:5]
	v_cndmask_b32_e64 v165, v145, v149, s[4:5]
	v_pk_fma_f32 v[234:235], v[164:165], v[204:205], v[234:235]
	v_pk_fma_f32 v[232:233], v[162:163], v[202:203], v[232:233]
	global_store_dwordx4 v[150:151], v[232:235], off
	ds_bpermute_b32 v142, v210, v36
	ds_bpermute_b32 v146, v210, v24
	ds_bpermute_b32 v143, v210, v37
	ds_bpermute_b32 v147, v210, v25
	ds_bpermute_b32 v144, v210, v38
	ds_bpermute_b32 v148, v210, v26
	ds_bpermute_b32 v145, v210, v39
	ds_bpermute_b32 v149, v210, v27
	s_waitcnt lgkmcnt(8)
	v_cndmask_b32_e64 v162, v178, v248, s[4:5]
	v_cndmask_b32_e64 v163, v179, v249, s[4:5]
	v_cndmask_b32_e64 v164, v180, v194, s[4:5]
	v_cndmask_b32_e64 v165, v181, v195, s[4:5]
	v_pk_fma_f32 v[238:239], v[164:165], v[204:205], v[238:239]
	v_pk_fma_f32 v[236:237], v[162:163], v[202:203], v[236:237]
	global_store_dwordx4 v[192:193], v[236:239], off
	ds_bpermute_b32 v178, v211, v36
	ds_bpermute_b32 v248, v211, v24
	ds_bpermute_b32 v179, v211, v37
	ds_bpermute_b32 v249, v211, v25
	ds_bpermute_b32 v180, v211, v38
	ds_bpermute_b32 v194, v211, v26
	ds_bpermute_b32 v181, v211, v39
	ds_bpermute_b32 v195, v211, v27
	s_waitcnt lgkmcnt(8)
	v_cndmask_b32_e64 v162, v142, v146, s[4:5]
	v_cndmask_b32_e64 v163, v143, v147, s[4:5]
	v_cndmask_b32_e64 v164, v144, v148, s[4:5]
	v_cndmask_b32_e64 v165, v145, v149, s[4:5]
	v_pk_fma_f32 v[242:243], v[164:165], v[208:209], v[242:243]
	v_pk_fma_f32 v[240:241], v[162:163], v[206:207], v[240:241]
	global_store_dwordx4 v[150:151], v[240:243], off offset:512
	ds_bpermute_b32 v142, v210, v32
	ds_bpermute_b32 v146, v210, v28
	ds_bpermute_b32 v143, v210, v33
	ds_bpermute_b32 v147, v210, v29
	ds_bpermute_b32 v144, v210, v34
	ds_bpermute_b32 v148, v210, v30
	ds_bpermute_b32 v145, v210, v35
	ds_bpermute_b32 v149, v210, v31
	s_waitcnt lgkmcnt(8)
	v_cndmask_b32_e64 v162, v178, v248, s[4:5]
	v_cndmask_b32_e64 v163, v179, v249, s[4:5]
	v_cndmask_b32_e64 v164, v180, v194, s[4:5]
	v_cndmask_b32_e64 v165, v181, v195, s[4:5]
	v_pk_fma_f32 v[246:247], v[164:165], v[208:209], v[246:247]
	v_pk_fma_f32 v[244:245], v[162:163], v[206:207], v[244:245]
	global_store_dwordx4 v[192:193], v[244:247], off offset:512
	v_lshl_add_u64 v[212:213], v[212:213], 0, s[24:25]
	v_lshl_add_u64 v[214:215], v[214:215], 0, s[24:25]
	global_load_dwordx4 v[232:235], v[212:213], off
	global_load_dwordx4 v[236:239], v[214:215], off
	global_load_dwordx4 v[240:243], v[212:213], off offset:512
	global_load_dwordx4 v[244:247], v[214:215], off offset:512
	ds_bpermute_b32 v178, v211, v32
	ds_bpermute_b32 v248, v211, v28
	ds_bpermute_b32 v179, v211, v33
	ds_bpermute_b32 v249, v211, v29
	ds_bpermute_b32 v180, v211, v34
	ds_bpermute_b32 v194, v211, v30
	ds_bpermute_b32 v181, v211, v35
	ds_bpermute_b32 v195, v211, v31
	s_waitcnt lgkmcnt(8)
; #define PG8_BAR __builtin_amdgcn_s_barrier()
; template <class Epi, class Sched, bool ALIGN_EPI = false, bool SP2 = false>
; __device__ __forceinline__ void gemm_phase(PG8_LAS unsigned char* lds, const Gemm g, const Sched& S, const Epi& E) {
;     ...
;         if constexpr (!Epi::AFTER_DRAIN) { E(acc, cur, wr, wc, fr, fq); S.done(cur); }
;         if (!has_next) break;
; #pragma unroll
;         for (int a = 0; a < 2; ++a)
; #pragma unroll
;             for (int b = 0; b < 2; ++b)
; #pragma unroll
;                 for (int m = 0; m < 4; ++m)
; #pragma unroll
;                     for (int n = 0; n < 2; ++n) acc[a][b][m][n] = (f32x4){0.f, 0.f, 0.f, 0.f};
;         cur = nxt; cA = nA; cB = nB; ++ui;
;         if constexpr (ALIGN_EPI) { if (wr == 1) PG8_BAR; }
;     }
;   DI void operator()(const pg8::f32x4 (&acc)[2][2][4][2], const pg8::Unit& u, int wr, int wc, int fr, int fq) const {
;     const int row0 = u.pm * 256 + wr * 64 + fr, col0 = u.pn * 256 + wc * 32 + 8 * fq;
;     const int b = (u.pm * 256) / TT;
; #pragma unroll
;     for (int ai = 0; ai < 2; ++ai)
; #pragma unroll
;       for (int m = 0; m < 4; ++m) {
;         const int row = row0 + ai * 128 + m * 16;
;         const int t = row - b * TT;
;         const bool isc = t >= TL;
;         float* dst = isc ? xc + ((size_t)b * TC + (t - TL)) * DM : xout + ((size_t)b * TL + t) * DM;
;         const float* src = src_input ? (isc ? cin + ((size_t)b * TC + (t - TL)) * DM : xin + ((size_t)b * TL + t) * DM) : dst;
;         const float* gate = modl + (size_t)(isc ? 16 : b) * 6144 + gi * DM;
; #pragma unroll
;         for (int bj = 0; bj < 2; ++bj) {
;           const int col = col0 + bj * 128;
; #pragma unroll
;           for (int n = 0; n < 2; ++n) {
;             pg8::f32x4 sv = *(const pg8::f32x4*)(src + col + 4 * n);
;             pg8::f32x4 gv = *(const pg8::f32x4*)(gate + col + 4 * n);
;             pg8::f32x4 o = sv + gv * acc[ai][bj][m][n];
;             *(pg8::f32x4*)(dst + col + 4 * n) = o;
;           }
;         }
;       }
;   }
	s_waitcnt vmcnt(8)
	v_lshl_add_u64 v[150:151], v[150:151], 0, s[24:25]
	v_lshl_add_u64 v[192:193], v[192:193], 0, s[24:25]
	v_cndmask_b32_e64 v162, v142, v146, s[4:5]
	v_cndmask_b32_e64 v163, v143, v147, s[4:5]
	v_cndmask_b32_e64 v164, v144, v148, s[4:5]
	v_cndmask_b32_e64 v165, v145, v149, s[4:5]
	v_pk_fma_f32 v[218:219], v[164:165], v[204:205], v[218:219]
	v_pk_fma_f32 v[216:217], v[162:163], v[202:203], v[216:217]
	global_store_dwordx4 v[150:151], v[216:219], off
	ds_bpermute_b32 v142, v210, v20
	ds_bpermute_b32 v146, v210, v8
	ds_bpermute_b32 v143, v210, v21
	ds_bpermute_b32 v147, v210, v9
	ds_bpermute_b32 v144, v210, v22
	ds_bpermute_b32 v148, v210, v10
	ds_bpermute_b32 v145, v210, v23
	ds_bpermute_b32 v149, v210, v11
	s_waitcnt lgkmcnt(8)
	v_cndmask_b32_e64 v162, v178, v248, s[4:5]
	v_cndmask_b32_e64 v163, v179, v249, s[4:5]
	v_cndmask_b32_e64 v164, v180, v194, s[4:5]
	v_cndmask_b32_e64 v165, v181, v195, s[4:5]
	v_pk_fma_f32 v[222:223], v[164:165], v[204:205], v[222:223]
	v_pk_fma_f32 v[220:221], v[162:163], v[202:203], v[220:221]
	global_store_dwordx4 v[192:193], v[220:223], off
	ds_bpermute_b32 v178, v211, v20
	ds_bpermute_b32 v248, v211, v8
	ds_bpermute_b32 v179, v211, v21
	ds_bpermute_b32 v249, v211, v9
	ds_bpermute_b32 v180, v211, v22
	ds_bpermute_b32 v194, v211, v10
	ds_bpermute_b32 v181, v211, v23
	ds_bpermute_b32 v195, v211, v11
	s_waitcnt lgkmcnt(8)
	v_cndmask_b32_e64 v162, v142, v146, s[4:5]
	v_cndmask_b32_e64 v163, v143, v147, s[4:5]
	v_cndmask_b32_e64 v164, v144, v148, s[4:5]
	v_cndmask_b32_e64 v165, v145, v149, s[4:5]
	v_pk_fma_f32 v[226:227], v[164:165], v[208:209], v[226:227]
	v_pk_fma_f32 v[224:225], v[162:163], v[206:207], v[224:225]
	global_store_dwordx4 v[150:151], v[224:227], off offset:512
	ds_bpermute_b32 v142, v210, v16
	ds_bpermute_b32 v146, v210, v12
	ds_bpermute_b32 v143, v210, v17
	ds_bpermute_b32 v147, v210, v13
	ds_bpermute_b32 v144, v210, v18
	ds_bpermute_b32 v148, v210, v14
	ds_bpermute_b32 v145, v210, v19
	ds_bpermute_b32 v149, v210, v15
	s_waitcnt lgkmcnt(8)
	v_cndmask_b32_e64 v162, v178, v248, s[4:5]
	v_cndmask_b32_e64 v163, v179, v249, s[4:5]
	v_cndmask_b32_e64 v164, v180, v194, s[4:5]
	v_cndmask_b32_e64 v165, v181, v195, s[4:5]
	v_pk_fma_f32 v[230:231], v[164:165], v[208:209], v[230:231]
	v_pk_fma_f32 v[228:229], v[162:163], v[206:207], v[228:229]
	global_store_dwordx4 v[192:193], v[228:231], off offset:512
	ds_bpermute_b32 v178, v211, v16
	ds_bpermute_b32 v248, v211, v12
	ds_bpermute_b32 v179, v211, v17
	ds_bpermute_b32 v249, v211, v13
	ds_bpermute_b32 v180, v211, v18
	ds_bpermute_b32 v194, v211, v14
	ds_bpermute_b32 v181, v211, v19
	ds_bpermute_b32 v195, v211, v15
	s_waitcnt lgkmcnt(8)
	s_waitcnt vmcnt(4)
	v_lshl_add_u64 v[150:151], v[150:151], 0, s[24:25]
	v_lshl_add_u64 v[192:193], v[192:193], 0, s[24:25]
	v_cndmask_b32_e64 v162, v142, v146, s[4:5]
	v_cndmask_b32_e64 v163, v143, v147, s[4:5]
	v_cndmask_b32_e64 v164, v144, v148, s[4:5]
	v_cndmask_b32_e64 v165, v145, v149, s[4:5]
	v_pk_fma_f32 v[234:235], v[164:165], v[204:205], v[234:235]
	v_pk_fma_f32 v[232:233], v[162:163], v[202:203], v[232:233]
	global_store_dwordx4 v[150:151], v[232:235], off
	ds_bpermute_b32 v142, v210, v4
	ds_bpermute_b32 v146, v210, v0
	ds_bpermute_b32 v143, v210, v5
	ds_bpermute_b32 v147, v210, v1
	ds_bpermute_b32 v144, v210, v6
	ds_bpermute_b32 v148, v210, v2
	ds_bpermute_b32 v145, v210, v7
	ds_bpermute_b32 v149, v210, v3
	s_waitcnt lgkmcnt(8)
	v_cndmask_b32_e64 v162, v178, v248, s[4:5]
	v_cndmask_b32_e64 v163, v179, v249, s[4:5]
	v_cndmask_b32_e64 v164, v180, v194, s[4:5]
	v_cndmask_b32_e64 v165, v181, v195, s[4:5]
	v_pk_fma_f32 v[238:239], v[164:165], v[204:205], v[238:239]
	v_pk_fma_f32 v[236:237], v[162:163], v[202:203], v[236:237]
	global_store_dwordx4 v[192:193], v[236:239], off
	ds_bpermute_b32 v178, v211, v4
	ds_bpermute_b32 v248, v211, v0
	ds_bpermute_b32 v179, v211, v5
	ds_bpermute_b32 v249, v211, v1
	ds_bpermute_b32 v180, v211, v6
	ds_bpermute_b32 v194, v211, v2
	ds_bpermute_b32 v181, v211, v7
	ds_bpermute_b32 v195, v211, v3
	s_waitcnt lgkmcnt(8)
	v_cndmask_b32_e64 v162, v142, v146, s[4:5]
	v_cndmask_b32_e64 v163, v143, v147, s[4:5]
	v_cndmask_b32_e64 v164, v144, v148, s[4:5]
	v_cndmask_b32_e64 v165, v145, v149, s[4:5]
	v_pk_fma_f32 v[242:243], v[164:165], v[208:209], v[242:243]
	v_pk_fma_f32 v[240:241], v[162:163], v[206:207], v[240:241]
	global_store_dwordx4 v[150:151], v[240:243], off offset:512
	s_waitcnt lgkmcnt(0)
	v_cndmask_b32_e64 v162, v178, v248, s[4:5]
	v_cndmask_b32_e64 v163, v179, v249, s[4:5]
	v_cndmask_b32_e64 v164, v180, v194, s[4:5]
	v_cndmask_b32_e64 v165, v181, v195, s[4:5]
	v_pk_fma_f32 v[246:247], v[164:165], v[208:209], v[246:247]
	v_pk_fma_f32 v[244:245], v[162:163], v[206:207], v[244:245]
	global_store_dwordx4 v[192:193], v[244:247], off offset:512
	s_and_b64 vcc, exec, s[2:3]
	s_mov_b64 s[2:3], -1
	s_cbranch_vccnz .LBB0_1496
	s_andn2_b64 vcc, exec, s[6:7]
	s_cbranch_vccnz .LBB0_1495
	s_barrier
	s_branch .LBB0_1495
